# v87 stack + stray vmcnt(0) between the conv weight loads removed + P0 memn row-sum all-reduce via DPP/permlane
# baseline (speedup 1.0000x reference)
; __device__ __forceinline__ unsigned pk2(float lo, float hi) { return pg8::cvt_pk_bf16(lo, hi); }
; __device__ __forceinline__ float wave_sum(float v) {
; #pragma unroll
;     for (int o = 1; o < 64; o <<= 1) v += __shfl_xor(v, o);
;     return v;
; }
; __global__ void __launch_bounds__(NWAVES * 64, 2) mk_fwd(Args args) {
;     ...
;         for (int m = gw; m < NB * ML; m += NGW) {
;             const f32x4* xr = (const f32x4*)(mem + (size_t)m * DM) + lane;
;             f32x4 v[4]; float s = 0.f;
; #pragma unroll
;             for (int j = 0; j < 4; ++j) { v[j] = xr[64 * j]; s += (v[j][0] * v[j][0] + v[j][1] * v[j][1]) + (v[j][2] * v[j][2] + v[j][3] * v[j][3]); }
;             const float rs = 1.0f / sqrtf(wave_sum(s) * (1.f / DM) + EPS);
;             unsigned long long* o8 = (unsigned long long*)(MEMN + (size_t)m * DM) + lane;
; #pragma unroll
;             for (int j = 0; j < 4; ++j) { v[j] = v[j] * rs * gg[j]; o8[64 * j] = (unsigned long long)pk2(v[j][0], v[j][1]) | ((unsigned long long)pk2(v[j][2], v[j][3]) << 32); }
;         }
.Lmemn_nopf:
	s_waitcnt lgkmcnt(0)
	v_pk_mul_f32 v[44:45], v[30:31], v[30:31]
	v_pk_mul_f32 v[46:47], v[28:29], v[28:29]
	v_pk_mul_f32 v[48:49], v[34:35], v[34:35]
	v_pk_mul_f32 v[50:51], v[32:33], v[32:33]
	v_pk_mov_b32 v[56:57], v[46:47], v[44:45] op_sel:[1,0]
	v_mov_b32_e32 v47, v45
	v_pk_mov_b32 v[44:45], v[50:51], v[48:49] op_sel:[1,0]
	v_mov_b32_e32 v51, v49
	v_mul_f32_e32 v55, v40, v40
	v_mul_f32_e32 v52, v37, v37
	v_mul_f32_e32 v54, v39, v39
	v_pk_add_f32 v[46:47], v[56:57], v[46:47]
	v_pk_add_f32 v[44:45], v[44:45], v[50:51]
	v_mul_f32_e32 v58, v41, v41
	v_mul_f32_e32 v59, v42, v42
	v_mul_f32_e32 v60, v43, v43
	v_pk_fma_f32 v[48:49], v[36:37], v[36:37], v[52:53] op_sel_hi:[1,1,0]
	v_pk_fma_f32 v[52:53], v[38:39], v[38:39], v[54:55] op_sel_hi:[1,1,0]
	v_pk_add_f32 v[46:47], v[46:47], v[46:47] op_sel:[0,1] op_sel_hi:[1,0]
	v_pk_add_f32 v[44:45], v[44:45], v[44:45] op_sel:[0,1] op_sel_hi:[1,0]
	v_mov_b32_e32 v49, v59
	v_mov_b32_e32 v53, v60
	v_mov_b32_e32 v47, v55
	v_mov_b32_e32 v45, v58
	v_pk_add_f32 v[48:49], v[48:49], v[52:53]
	v_pk_add_f32 v[44:45], v[46:47], v[44:45]
	s_nop 0
	v_pk_add_f32 v[44:45], v[44:45], v[48:49]
	s_nop 0
	v_add_f32_e32 v44, v44, v45
	s_nop 1
	v_add_f32_dpp v44, v44, v44 quad_perm:[1,0,3,2] row_mask:0xf bank_mask:0xf
	s_nop 1
	v_add_f32_dpp v44, v44, v44 quad_perm:[2,3,0,1] row_mask:0xf bank_mask:0xf
	s_nop 1
	v_add_f32_dpp v44, v44, v44 row_half_mirror row_mask:0xf bank_mask:0xf
	s_nop 1
	v_add_f32_dpp v44, v44, v44 row_mirror row_mask:0xf bank_mask:0xf
	v_mov_b32_e32 v45, v44
	s_nop 1
	v_permlane16_swap_b32_e32 v44, v45
	v_add_f32_e32 v44, v44, v45
	v_mov_b32_e32 v45, v44
	s_nop 1
	v_permlane32_swap_b32_e32 v44, v45
	v_add_f32_e32 v44, v44, v45
	v_fmamk_f32 v44, v44, 0x3a800000, v26
	v_mul_f32_e32 v45, 0x4f800000, v44
	v_cmp_gt_f32_e32 vcc, s3, v44
	s_nop 1
	v_cndmask_b32_e32 v44, v44, v45, vcc
	v_sqrt_f32_e32 v45, v44
	s_nop 0
	v_add_u32_e32 v46, -1, v45
	v_add_u32_e32 v47, 1, v45
	v_fma_f32 v48, -v46, v45, v44
	v_fma_f32 v49, -v47, v45, v44
	v_cmp_ge_f32_e64 s[4:5], 0, v48
	s_nop 1
	v_cndmask_b32_e64 v45, v45, v46, s[4:5]
	v_cmp_lt_f32_e64 s[4:5], 0, v49
	s_nop 1
	v_cndmask_b32_e64 v45, v45, v47, s[4:5]
	v_mul_f32_e32 v46, 0x37800000, v45
	v_cndmask_b32_e32 v45, v45, v46, vcc
	v_cmp_class_f32_e32 vcc, v44, v27
	s_nop 1
	v_cndmask_b32_e32 v44, v45, v44, vcc
	v_div_scale_f32 v45, s[4:5], v44, v44, 1.0
	v_rcp_f32_e32 v47, v45
	v_div_scale_f32 v46, vcc, 1.0, v44, 1.0
	v_fma_f32 v48, -v45, v47, 1.0
	v_fmac_f32_e32 v47, v48, v47
	v_mul_f32_e32 v48, v46, v47
	v_fma_f32 v49, -v45, v48, v46
	v_fmac_f32_e32 v48, v49, v47
	v_fma_f32 v45, -v45, v48, v46
	v_div_fmas_f32 v45, v45, v47, v48
	v_div_fixup_f32 v44, v45, v44, 1.0
	v_pk_mul_f32 v[28:29], v[44:45], v[28:29] op_sel_hi:[0,1]
	v_pk_mul_f32 v[30:31], v[44:45], v[30:31] op_sel_hi:[0,1]
	v_pk_mul_f32 v[28:29], v[28:29], v[0:1]
	v_pk_mul_f32 v[32:33], v[44:45], v[32:33] op_sel_hi:[0,1]
	v_pk_mul_f32 v[34:35], v[44:45], v[34:35] op_sel_hi:[0,1]
	v_pk_mul_f32 v[30:31], v[30:31], v[2:3]
	v_cvt_pk_bf16_f32 v28, v28, v29
	v_pk_mul_f32 v[36:37], v[44:45], v[36:37] op_sel_hi:[0,1]
	v_cvt_pk_bf16_f32 v29, v30, v31
	v_pk_mul_f32 v[38:39], v[44:45], v[38:39] op_sel_hi:[0,1]
	v_pk_mul_f32 v[34:35], v[34:35], v[6:7]
	v_pk_mul_f32 v[32:33], v[32:33], v[4:5]
	flat_store_dwordx2 v[16:17], v[28:29]
	v_cvt_pk_bf16_f32 v28, v32, v33
	v_cvt_pk_bf16_f32 v29, v34, v35
	v_pk_mul_f32 v[40:41], v[44:45], v[40:41] op_sel_hi:[0,1]
	v_pk_mul_f32 v[42:43], v[44:45], v[42:43] op_sel_hi:[0,1]
	v_pk_mul_f32 v[38:39], v[38:39], v[10:11]
	v_pk_mul_f32 v[36:37], v[36:37], v[8:9]
	flat_store_dwordx2 v[16:17], v[28:29] offset:512
	v_cvt_pk_bf16_f32 v28, v36, v37
	v_cvt_pk_bf16_f32 v29, v38, v39
	v_pk_mul_f32 v[42:43], v[42:43], v[14:15]
	v_pk_mul_f32 v[40:41], v[40:41], v[12:13]
	flat_store_dwordx2 v[16:17], v[28:29] offset:1024
	v_cvt_pk_bf16_f32 v28, v40, v41
	v_cvt_pk_bf16_f32 v29, v42, v43
	flat_store_dwordx2 v[16:17], v[28:29] offset:1536
	v_lshl_add_u64 v[16:17], v[16:17], 0, s[6:7]
	s_cbranch_scc0 .LBB0_43

; #define LAS __attribute__((address_space(3)))
; __global__ void __launch_bounds__(NWAVES * 64, 2) mk_fwd(Args args) {
;     ...
;             const int cp = tid & 255, th = tid >> 8;
;             f32x2 w[31];
; #pragma unroll
;             for (int j = 0; j < 31; ++j) w[j] = *(const f32x2*)(conv_w + j * 512 + 2 * cp);
;             const f32x2 cb = *(const f32x2*)(conv_b + 2 * cp);
;             LAS float* yt = (LAS float*)lds;
;             f32x4 lg0 = *(const f32x4*)(ln_g + 4 * lane), lg1 = *(const f32x4*)(ln_g + 256 + 4 * lane), lb0 = *(const f32x4*)(ln_b + 4 * lane), lb1 = *(const f32x4*)(ln_b + 256 + 4 * lane);
.LBB0_352:
	s_lshl_b32 s4, s73, 1
	s_andn2_b32 s4, s4, 63
	s_and_b32 s5, s73, 31
	s_or_b32 s4, s4, s5
	s_and_b64 s[6:7], s[50:51], exec
	s_cselect_b32 s6, s4, s73
	s_cmpk_lt_i32 s6, 0x200
	s_cbranch_scc0 .LBB0_361
	v_lshlrev_b32_e32 v0, 1, v200
	v_and_b32_e32 v20, 0x1fe, v0
	v_mov_b32_e32 v80, 0
	v_lshlrev_b32_e32 v0, 2, v20
	v_mov_b32_e32 v1, v80
	v_lshl_add_u64 v[2:3], s[18:19], 0, v[0:1]
	v_add_co_u32_e32 v4, vcc, 0x1000, v2
	v_lshl_add_u64 v[0:1], s[16:17], 0, v[0:1]
	s_nop 0
	v_addc_co_u32_e32 v5, vcc, 0, v3, vcc
	flat_load_dwordx2 v[82:83], v[2:3]
	flat_load_dwordx2 v[84:85], v[2:3] offset:2048
	flat_load_dwordx2 v[86:87], v[4:5]
	flat_load_dwordx2 v[88:89], v[4:5] offset:2048
	v_add_co_u32_e32 v4, vcc, 0x2000, v2
	v_mov_b32_e32 v17, v80
	s_nop 0
	v_addc_co_u32_e32 v5, vcc, 0, v3, vcc
	v_add_co_u32_e32 v6, vcc, 0x3000, v2
	s_ashr_i32 s5, s72, 6
	s_nop 0
	v_addc_co_u32_e32 v7, vcc, 0, v3, vcc
	flat_load_dwordx2 v[90:91], v[4:5]
	flat_load_dwordx2 v[92:93], v[4:5] offset:2048
	flat_load_dwordx2 v[94:95], v[6:7]
	flat_load_dwordx2 v[96:97], v[6:7] offset:2048
	v_add_co_u32_e32 v4, vcc, 0x4000, v2
	s_movk_i32 s7, 0x1000
	s_nop 0
	v_addc_co_u32_e32 v5, vcc, 0, v3, vcc
	v_add_co_u32_e32 v6, vcc, 0x5000, v2
	s_movk_i32 s8, 0x2000
	s_nop 0
	v_addc_co_u32_e32 v7, vcc, 0, v3, vcc
	flat_load_dwordx2 v[98:99], v[4:5]
	s_nop 0
	flat_load_dwordx2 v[100:101], v[4:5] offset:2048
	flat_load_dwordx2 v[102:103], v[6:7]
	flat_load_dwordx2 v[104:105], v[6:7] offset:2048
	v_add_co_u32_e32 v4, vcc, 0x6000, v2
	s_movk_i32 s9, 0x3000
	s_nop 0
	v_addc_co_u32_e32 v5, vcc, 0, v3, vcc
	v_add_co_u32_e32 v6, vcc, 0x7000, v2
	v_mov_b32_e32 v176, 0x358637bd
	s_nop 0
	v_addc_co_u32_e32 v7, vcc, 0, v3, vcc
	flat_load_dwordx2 v[106:107], v[4:5]
	flat_load_dwordx2 v[108:109], v[4:5] offset:2048
	flat_load_dwordx2 v[110:111], v[6:7]
	flat_load_dwordx2 v[112:113], v[6:7] offset:2048
	v_add_co_u32_e32 v4, vcc, 0x8000, v2
	v_mov_b32_e32 v177, 0x260
	s_nop 0
	v_addc_co_u32_e32 v5, vcc, 0, v3, vcc
	v_add_co_u32_e32 v6, vcc, 0x9000, v2
	s_nop 1
	v_addc_co_u32_e32 v7, vcc, 0, v3, vcc
	flat_load_dwordx2 v[114:115], v[4:5]
	flat_load_dwordx2 v[116:117], v[4:5] offset:2048
	flat_load_dwordx2 v[118:119], v[6:7]
	flat_load_dwordx2 v[120:121], v[6:7] offset:2048
	v_add_co_u32_e32 v4, vcc, 0xa000, v2
	s_nop 1
	v_addc_co_u32_e32 v5, vcc, 0, v3, vcc
	v_add_co_u32_e32 v6, vcc, 0xb000, v2
	s_nop 1
	v_addc_co_u32_e32 v7, vcc, 0, v3, vcc
	flat_load_dwordx2 v[122:123], v[4:5]
	flat_load_dwordx2 v[124:125], v[4:5] offset:2048
	flat_load_dwordx2 v[126:127], v[6:7]
	flat_load_dwordx2 v[128:129], v[6:7] offset:2048
	v_add_co_u32_e32 v4, vcc, 0xc000, v2
	s_nop 1
	v_addc_co_u32_e32 v5, vcc, 0, v3, vcc
	v_add_co_u32_e32 v6, vcc, 0xd000, v2
	s_nop 1
	v_addc_co_u32_e32 v7, vcc, 0, v3, vcc
	flat_load_dwordx2 v[130:131], v[4:5]
	flat_load_dwordx2 v[132:133], v[4:5] offset:2048
	flat_load_dwordx2 v[134:135], v[6:7]
	flat_load_dwordx2 v[136:137], v[6:7] offset:2048
	v_add_co_u32_e32 v4, vcc, 0xe000, v2
	s_nop 1
	v_addc_co_u32_e32 v5, vcc, 0, v3, vcc
	v_add_co_u32_e32 v2, vcc, 0xf000, v2
	s_nop 1
	v_addc_co_u32_e32 v3, vcc, 0, v3, vcc
	flat_load_dwordx2 v[138:139], v[4:5]
	flat_load_dwordx2 v[140:141], v[4:5] offset:2048
	flat_load_dwordx2 v[142:143], v[2:3]
	flat_load_dwordx2 v[144:145], v[0:1]
	v_lshlrev_b32_e32 v0, 2, v200
	v_and_b32_e32 v21, 0xfc, v0
	v_lshlrev_b32_e32 v16, 2, v21
	v_lshl_add_u64 v[8:9], s[12:13], 0, v[16:17]
	v_lshl_add_u64 v[18:19], s[14:15], 0, v[16:17]
	flat_load_dwordx4 v[0:3], v[8:9]
	flat_load_dwordx4 v[4:7], v[8:9] offset:1024
	s_nop 0
	flat_load_dwordx4 v[8:11], v[18:19]
	flat_load_dwordx4 v[12:15], v[18:19] offset:1024
	v_lshlrev_b32_e32 v18, 1, v20
	v_mov_b32_e32 v19, v80
	v_lshl_add_u64 v[18:19], s[2:3], 0, v[18:19]
	s_mov_b64 s[14:15], 0x8000000
	v_mbcnt_lo_u32_b32 v17, -1, 0
	v_lshl_add_u64 v[146:147], v[18:19], 0, s[14:15]
	s_or_b32 s15, s4, 32
	s_lshl_b32 s4, s5, 14
	v_mbcnt_hi_u32_b32 v17, -1, v17
	s_add_i32 s4, s4, 0
	v_and_b32_e32 v19, 64, v17
	v_add_u32_e32 v19, 64, v19
	v_add_u32_e32 v168, s4, v16
	v_xor_b32_e32 v16, 1, v17
	v_cmp_lt_i32_e32 vcc, v16, v19
	s_lshl_b32 s14, s5, 3
	s_mov_b64 s[4:5], 0x14000000
	v_cndmask_b32_e32 v16, v17, v16, vcc
	v_lshlrev_b32_e32 v169, 2, v16
	v_xor_b32_e32 v16, 2, v17
	v_cmp_lt_i32_e32 vcc, v16, v19
	v_ashrrev_i32_e32 v18, 3, v200
	v_and_b32_e32 v166, 0xffffffe0, v18
	v_cndmask_b32_e32 v16, v17, v16, vcc
	v_lshlrev_b32_e32 v170, 2, v16
	v_xor_b32_e32 v16, 4, v17
	v_cmp_lt_i32_e32 vcc, v16, v19
	s_mov_b32 s13, 0
	s_movk_i32 s12, 0x5000
	v_cndmask_b32_e32 v16, v17, v16, vcc
	v_lshlrev_b32_e32 v171, 2, v16
	v_xor_b32_e32 v16, 8, v17
	v_cmp_lt_i32_e32 vcc, v16, v19
	v_sub_u32_e32 v167, 0, v166
	s_nop 0
	v_cndmask_b32_e32 v16, v17, v16, vcc
	v_lshlrev_b32_e32 v172, 2, v16
	v_xor_b32_e32 v16, 16, v17
	v_cmp_lt_i32_e32 vcc, v16, v19
	s_nop 1
	v_cndmask_b32_e32 v16, v17, v16, vcc
	v_lshlrev_b32_e32 v173, 2, v16
	v_xor_b32_e32 v16, 32, v17
	v_cmp_lt_i32_e32 vcc, v16, v19
	s_nop 1
	v_cndmask_b32_e32 v16, v17, v16, vcc
	v_lshlrev_b32_e32 v174, 2, v16
	v_lshlrev_b32_e32 v16, 1, v21
	v_mov_b32_e32 v17, v80
	v_lshl_add_u64 v[16:17], s[10:11], 0, v[16:17]
	v_lshl_add_u64 v[148:149], v[16:17], 0, s[4:5]
	v_mov_b32_e32 v16, 2
	v_lshlrev_b32_sdwa v16, v16, v200 dst_sel:DWORD dst_unused:UNUSED_PAD src0_sel:DWORD src1_sel:BYTE_0
	v_mov_b32_e32 v17, v80
	v_lshl_add_u64 v[150:151], s[2:3], 0, v[16:17]
	v_mov_b32_e32 v17, 3
	v_lshlrev_b32_e32 v16, 11, v18
	v_lshlrev_b32_sdwa v17, v17, v200 dst_sel:DWORD dst_unused:UNUSED_PAD src0_sel:DWORD src1_sel:BYTE_0
	s_mov_b32 s2, 0xffff0000
	v_and_or_b32 v16, v16, s2, v17
	v_add_u32_e32 v175, 0, v16
	s_movk_i32 s10, 0x1400
	s_mov_b32 s11, 0xf800000
	s_branch .LBB0_355
